# v27 plus one static s_setprio 1 for waves 4-7 during the attention phase (strategy: static priority raise for the younger half)
# speedup vs baseline: 1.0028x; 1.0028x over previous
; DI int obid() { int b = blockIdx.x; asm volatile("" : "+s"(b)); return b; }
; DI KParams kp() { KParams k = (KParams)__builtin_amdgcn_kernarg_segment_ptr(); asm volatile("" : "+s"(k)); return k; }
; #define TILE_LOOP(q, x, NPX) for (int lin_ = (nb == 256 ? (bid >> 3) : bid), q = (nb == 256 ? lin_ : lin_ / 8), x = (nb == 256 ? (bid & 7) : lin_ % 8); \
;     (nb == 256 ? q < (NPX) : lin_ < 8 * (NPX)); lin_ += (nb == 256 ? 32 : nb), q = (nb == 256 ? lin_ : lin_ / 8), x = (nb == 256 ? x : lin_ % 8))
; DI void phase_att_attn(char* smem) {
;   KParams P = kp(); char* ws = P->ws;
;   const int nb = gridDim.x, bid = obid();
;   const u16* QKV = GBP(u16, A_QKV); u16* Ob = GBP(u16, A_O);
;   TILE_LOOP(q, x, 128) {
;     const int cb = (q >> 6) * 8 + x, sl = cb >> 1, kvh = cb & 1, hq = kvh * 4 + ((q >> 4) & 3), qb = q & 15;
.LBB0_1147:
	s_ashr_i32 s13, s12, 3
	s_and_b64 s[10:11], s[6:7], exec
	s_cselect_b32 s61, s13, s12
	s_ashr_i32 s10, s61, 31
	s_lshr_b32 s10, s10, 29
	s_add_i32 s10, s61, s10
	s_ashr_i32 s12, s10, 3
	s_and_b64 s[10:11], s[6:7], exec
	s_cselect_b32 s10, s13, s12
	s_cmpk_lt_i32 s10, 0x80
	s_cselect_b64 s[12:13], -1, 0
	s_cmpk_lt_i32 s61, 0x400
	v_cndmask_b32_e64 v0, 0, 1, s[12:13]
	s_cselect_b64 s[12:13], -1, 0
	v_cndmask_b32_e64 v1, 0, 1, s[12:13]
	v_cndmask_b32_e64 v0, v1, v0, s[6:7]
	v_and_b32_e32 v0, 1, v0
	v_cmp_eq_u32_e32 vcc, 0, v0
	s_cbranch_vccnz .LBB0_1170
	s_waitcnt lgkmcnt(0)
	v_readfirstlane_b32 vcc_lo, v182
	s_nop 3
	s_lshr_b32 vcc_lo, vcc_lo, 6
	s_cmp_ge_u32 vcc_lo, 4
	s_cbranch_scc0 .Latt_prio_done
	s_setprio 1
.Latt_prio_done:
	s_add_u32 s72, s8, 0x762c100
	s_addc_u32 s73, s9, 0
	s_add_u32 s74, s8, 0xd62c100
	s_addc_u32 s75, s9, 0
	s_add_u32 s12, s8, 0x7704b00
	s_addc_u32 s13, s9, 0
	s_branch .LBB0_1150

; __device__ __forceinline__ unsigned xb_ld(unsigned* p)              { return __hip_atomic_load(p, __ATOMIC_RELAXED, __HIP_MEMORY_SCOPE_AGENT); }
; __device__ __forceinline__ void xcd_barrier_complete(unsigned* bar, unsigned x, unsigned& nloc, unsigned& nx) {
;     const unsigned G = gridDim.x * gridDim.y * gridDim.z;
;     unsigned sum, cnt, mine, sp = 0u;
;     for (;;) {
;         sum = 0u; cnt = 0u; mine = 0u;
; #pragma unroll
;         for (unsigned j = 0; j < 16; ++j) { const unsigned c = xb_ld(&bar[XB_XCNT(j)]); sum += c; cnt += (c > 0u) ? 1u : 0u; mine = (j == x) ? c : mine; }
; __device__ __forceinline__ void xcd_barrier(const XcdBarrier& b) {
;     asm volatile("s_waitcnt vmcnt(0)" ::: "memory");
;     __syncthreads();
;     if (threadIdx.x == 0) {
;         unsigned* bar = b.bar;
;         __builtin_amdgcn_s_waitcnt(0);
;         unsigned nloc = b.st[0], nx = b.st[1];
;         if (nloc == 0u) { xcd_barrier_complete(bar, b.x, nloc, nx); b.st[0] = nloc; b.st[1] = nx; }
.LBB0_1170:
	s_setprio 0
	s_mov_b64 s[10:11], s[96:97]
	s_getreg_b32 s12, hwreg(HW_REG_XCC_ID, 0, 4)
	s_waitcnt vmcnt(0)
	s_waitcnt lgkmcnt(0)
	s_barrier
	s_and_saveexec_b64 s[8:9], s[84:85]
	s_cbranch_execz .LBB0_1222
	s_load_dwordx2 s[10:11], s[10:11], 0x98
	s_waitcnt vmcnt(0) expcnt(0) lgkmcnt(0)
	ds_read_b32 v2, v177
	ds_read_b32 v0, v177 offset:4
	s_and_b32 s17, s12, 15
	s_waitcnt lgkmcnt(1)
	v_cmp_ne_u32_e32 vcc, 0, v2
	s_cbranch_vccnz .LBB0_1186
	s_add_u32 s12, s10, 0x2b62c300
	s_addc_u32 s13, s11, 0
	s_add_u32 s18, s10, 0x2b62c500
	s_addc_u32 s19, s11, 0
	s_add_u32 s20, s10, 0x2b62c600
	s_addc_u32 s21, s11, 0
	s_add_u32 s22, s10, 0x2b62c700
	s_addc_u32 s23, s11, 0
	s_add_u32 s24, s10, 0x2b62c800
	s_addc_u32 s25, s11, 0
	s_add_u32 s26, s10, 0x2b62c900
	s_addc_u32 s27, s11, 0
	s_add_u32 s28, s10, 0x2b62ca00
	s_addc_u32 s29, s11, 0
	s_add_u32 s30, s10, 0x2b62cb00
	s_addc_u32 s31, s11, 0
	s_add_u32 s70, s10, 0x2b62cc00
	s_addc_u32 s71, s11, 0
	s_add_u32 s72, s10, 0x2b62cd00
	s_addc_u32 s73, s11, 0
	s_add_u32 s74, s10, 0x2b62ce00
	s_addc_u32 s75, s11, 0
	s_add_u32 s76, s10, 0x2b62cf00
	s_addc_u32 s77, s11, 0
	s_add_u32 s78, s10, 0x2b62d000
	s_addc_u32 s79, s11, 0
	s_add_u32 s80, s10, 0x2b62d100
	s_addc_u32 s81, s11, 0
	s_add_u32 s82, s10, 0x2b62d200
	s_addc_u32 s83, s11, 0
	s_add_u32 s84, s10, 0x2b62d300
	s_addc_u32 s85, s11, 0
	s_add_u32 s86, s10, 0x2b62d400
	s_mov_b32 s5, s89
	s_addc_u32 s87, s11, 0
	s_mov_b32 s92, 1
	s_branch .LBB0_1174
